# grid barrier: non-leader workgroups poll the top-level generation word directly (one fewer flag hop per barrier)
# speedup vs baseline: 1.0088x; 1.0012x over previous
.LBB0_229:
	s_or_b64 exec, exec, s[10:11]
	v_cvt_f32_u32_e32 v4, v2
	s_waitcnt vmcnt(0)
	v_readfirstlane_b32 s1, v3
	v_sub_u32_e32 v3, 0, v2
	v_rcp_iflag_f32_e32 v4, v4
	v_add_u32_e32 v5, s1, v1
	v_mul_f32_e32 v4, 0x4f7ffffe, v4
	v_cvt_u32_f32_e32 v4, v4
	v_mul_lo_u32 v1, v3, v4
	v_mul_hi_u32 v1, v4, v1
	v_add_u32_e32 v1, v4, v1
	v_mul_hi_u32 v1, v5, v1
	v_mul_lo_u32 v3, v1, v2
	v_sub_u32_e32 v3, v5, v3
	v_add_u32_e32 v4, 1, v1
	v_cmp_ge_u32_e32 vcc, v3, v2
	s_nop 1
	v_cndmask_b32_e32 v1, v1, v4, vcc
	v_sub_u32_e32 v4, v3, v2
	v_cndmask_b32_e32 v3, v3, v4, vcc
	v_add_u32_e32 v4, 1, v1
	v_cmp_ge_u32_e32 vcc, v3, v2
	v_add_u32_e32 v3, 1, v5
	s_nop 0
	v_cndmask_b32_e32 v1, v1, v4, vcc
	v_mul_lo_u32 v4, v2, v1
	v_add_u32_e32 v2, v4, v2
	v_cmp_ne_u32_e32 vcc, v3, v2
	s_and_saveexec_b64 s[2:3], vcc
	s_xor_b64 s[8:9], exec, s[2:3]
	s_cbranch_execz .LBB0_243
	s_movk_i32 s2, 0xd40
	s_mov_b32 s3, 0
	s_lshl_b64 s[2:3], s[2:3], 2
	v_readlane_b32 s10, v253, 10
	v_readlane_b32 s11, v253, 11
	s_add_u32 s14, s10, s2
	s_addc_u32 s15, s11, s3
	s_waitcnt lgkmcnt(0)
	v_mov_b32_e32 v0, 0
	global_load_dword v2, v0, s[14:15] sc1
	s_waitcnt vmcnt(0)
	v_cmp_eq_u32_e32 vcc, v2, v1
	s_and_saveexec_b64 s[10:11], vcc
	s_cbranch_execz .LBB0_242
	s_add_u32 s12, s4, 0x137daa00
	s_addc_u32 s13, s5, 0
	s_mov_b32 s1, 1
	s_mov_b64 s[16:17], 0
	s_branch .LBB0_233

.LBB0_1575:
	s_or_b64 exec, exec, s[8:9]
	v_cvt_f32_u32_e32 v4, v2
	s_waitcnt vmcnt(0)
	v_readfirstlane_b32 s1, v3
	v_sub_u32_e32 v3, 0, v2
	v_rcp_iflag_f32_e32 v4, v4
	v_add_u32_e32 v5, s1, v1
	v_mul_f32_e32 v4, 0x4f7ffffe, v4
	v_cvt_u32_f32_e32 v4, v4
	v_mul_lo_u32 v1, v3, v4
	v_mul_hi_u32 v1, v4, v1
	v_add_u32_e32 v1, v4, v1
	v_mul_hi_u32 v1, v5, v1
	v_mul_lo_u32 v3, v1, v2
	v_sub_u32_e32 v3, v5, v3
	v_add_u32_e32 v4, 1, v1
	v_cmp_ge_u32_e32 vcc, v3, v2
	s_nop 1
	v_cndmask_b32_e32 v1, v1, v4, vcc
	v_sub_u32_e32 v4, v3, v2
	v_cndmask_b32_e32 v3, v3, v4, vcc
	v_add_u32_e32 v4, 1, v1
	v_cmp_ge_u32_e32 vcc, v3, v2
	v_add_u32_e32 v3, 1, v5
	s_nop 0
	v_cndmask_b32_e32 v1, v1, v4, vcc
	v_mul_lo_u32 v4, v2, v1
	v_add_u32_e32 v2, v4, v2
	v_cmp_ne_u32_e32 vcc, v3, v2
	s_and_saveexec_b64 s[6:7], vcc
	s_xor_b64 s[6:7], exec, s[6:7]
	s_cbranch_execz .LBB0_1589
	s_movk_i32 s92, 0xd40
	s_lshl_b64 s[8:9], s[92:93], 2
	v_readlane_b32 s10, v253, 10
	v_readlane_b32 s11, v253, 11
	s_add_u32 s10, s10, s8
	s_addc_u32 s11, s11, s9
	s_waitcnt lgkmcnt(0)
	s_nop 1
	global_load_dword v0, v193, s[10:11] sc1
	s_waitcnt vmcnt(0)
	v_cmp_eq_u32_e32 vcc, v0, v1
	s_and_saveexec_b64 s[8:9], vcc
	s_cbranch_execz .LBB0_1588
	s_mov_b32 s1, 1
	s_mov_b64 s[12:13], 0
	s_branch .LBB0_1579

.LBB0_2244:
	s_or_b64 exec, exec, s[12:13]
	v_cvt_f32_u32_e32 v4, v2
	s_waitcnt vmcnt(0)
	v_readfirstlane_b32 s1, v3
	v_sub_u32_e32 v3, 0, v2
	v_rcp_iflag_f32_e32 v4, v4
	v_add_u32_e32 v5, s1, v1
	v_mul_f32_e32 v4, 0x4f7ffffe, v4
	v_cvt_u32_f32_e32 v4, v4
	v_mul_lo_u32 v1, v3, v4
	v_mul_hi_u32 v1, v4, v1
	v_add_u32_e32 v1, v4, v1
	v_mul_hi_u32 v1, v5, v1
	v_mul_lo_u32 v3, v1, v2
	v_sub_u32_e32 v3, v5, v3
	v_add_u32_e32 v4, 1, v1
	v_cmp_ge_u32_e32 vcc, v3, v2
	s_nop 1
	v_cndmask_b32_e32 v1, v1, v4, vcc
	v_sub_u32_e32 v4, v3, v2
	v_cndmask_b32_e32 v3, v3, v4, vcc
	v_add_u32_e32 v4, 1, v1
	v_cmp_ge_u32_e32 vcc, v3, v2
	v_add_u32_e32 v3, 1, v5
	s_nop 0
	v_cndmask_b32_e32 v1, v1, v4, vcc
	v_mul_lo_u32 v4, v2, v1
	v_add_u32_e32 v2, v4, v2
	v_cmp_ne_u32_e32 vcc, v3, v2
	s_and_saveexec_b64 s[8:9], vcc
	s_xor_b64 s[8:9], exec, s[8:9]
	s_cbranch_execz .LBB0_2258
	s_movk_i32 s12, 0xd40
	s_mov_b32 s13, s93
	s_lshl_b64 s[12:13], s[12:13], 2
	v_readlane_b32 s14, v253, 10
	v_readlane_b32 s15, v253, 11
	s_add_u32 s14, s14, s12
	s_addc_u32 s15, s15, s13
	s_waitcnt lgkmcnt(0)
	s_nop 1
	global_load_dword v0, v193, s[14:15] sc1
	s_waitcnt vmcnt(0)
	v_cmp_eq_u32_e32 vcc, v0, v1
	s_and_saveexec_b64 s[12:13], vcc
	s_cbranch_execz .LBB0_2257
	s_mov_b32 s1, 1
	s_mov_b64 s[22:23], 0
	s_branch .LBB0_2248

.LBB0_2354:
	s_or_b64 exec, exec, s[10:11]
	v_cvt_f32_u32_e32 v4, v2
	s_waitcnt vmcnt(0)
	v_readfirstlane_b32 s1, v3
	v_sub_u32_e32 v3, 0, v2
	v_rcp_iflag_f32_e32 v4, v4
	v_add_u32_e32 v5, s1, v1
	v_mul_f32_e32 v4, 0x4f7ffffe, v4
	v_cvt_u32_f32_e32 v4, v4
	v_mul_lo_u32 v1, v3, v4
	v_mul_hi_u32 v1, v4, v1
	v_add_u32_e32 v1, v4, v1
	v_mul_hi_u32 v1, v5, v1
	v_mul_lo_u32 v3, v1, v2
	v_sub_u32_e32 v3, v5, v3
	v_add_u32_e32 v4, 1, v1
	v_cmp_ge_u32_e32 vcc, v3, v2
	s_nop 1
	v_cndmask_b32_e32 v1, v1, v4, vcc
	v_sub_u32_e32 v4, v3, v2
	v_cndmask_b32_e32 v3, v3, v4, vcc
	v_add_u32_e32 v4, 1, v1
	v_cmp_ge_u32_e32 vcc, v3, v2
	v_add_u32_e32 v3, 1, v5
	s_nop 0
	v_cndmask_b32_e32 v1, v1, v4, vcc
	v_mul_lo_u32 v4, v2, v1
	v_add_u32_e32 v2, v4, v2
	v_cmp_ne_u32_e32 vcc, v3, v2
	s_and_saveexec_b64 s[8:9], vcc
	s_xor_b64 s[8:9], exec, s[8:9]
	s_cbranch_execz .LBB0_2368
	s_movk_i32 s92, 0xd40
	s_lshl_b64 s[10:11], s[92:93], 2
	v_readlane_b32 s12, v253, 10
	v_readlane_b32 s13, v253, 11
	s_add_u32 s12, s12, s10
	s_addc_u32 s13, s13, s11
	s_waitcnt lgkmcnt(0)
	s_nop 1
	global_load_dword v0, v193, s[12:13] sc1
	s_waitcnt vmcnt(0)
	v_cmp_eq_u32_e32 vcc, v0, v1
	s_and_saveexec_b64 s[10:11], vcc
	s_cbranch_execz .LBB0_2367
	s_mov_b32 s1, 1
	s_mov_b64 s[14:15], 0
	s_branch .LBB0_2358

.LBB0_3570:
	s_or_b64 exec, exec, s[6:7]
	v_cvt_f32_u32_e32 v4, v2
	s_waitcnt vmcnt(0)
	v_readfirstlane_b32 s4, v3
	v_sub_u32_e32 v3, 0, v2
	v_rcp_iflag_f32_e32 v4, v4
	v_add_u32_e32 v5, s4, v1
	v_mul_f32_e32 v4, 0x4f7ffffe, v4
	v_cvt_u32_f32_e32 v4, v4
	v_mul_lo_u32 v1, v3, v4
	v_mul_hi_u32 v1, v4, v1
	v_add_u32_e32 v1, v4, v1
	v_mul_hi_u32 v1, v5, v1
	v_mul_lo_u32 v3, v1, v2
	v_sub_u32_e32 v3, v5, v3
	v_add_u32_e32 v4, 1, v1
	v_cmp_ge_u32_e32 vcc, v3, v2
	s_nop 1
	v_cndmask_b32_e32 v1, v1, v4, vcc
	v_sub_u32_e32 v4, v3, v2
	v_cndmask_b32_e32 v3, v3, v4, vcc
	v_add_u32_e32 v4, 1, v1
	v_cmp_ge_u32_e32 vcc, v3, v2
	v_add_u32_e32 v3, 1, v5
	s_nop 0
	v_cndmask_b32_e32 v1, v1, v4, vcc
	v_mul_lo_u32 v4, v2, v1
	v_add_u32_e32 v2, v4, v2
	v_cmp_ne_u32_e32 vcc, v3, v2
	s_and_saveexec_b64 s[4:5], vcc
	s_xor_b64 s[4:5], exec, s[4:5]
	s_cbranch_execz .LBB0_3584
	s_movk_i32 s92, 0xd40
	s_lshl_b64 s[6:7], s[92:93], 2
	v_readlane_b32 s8, v253, 10
	v_readlane_b32 s9, v253, 11
	s_add_u32 s8, s8, s6
	s_addc_u32 s9, s9, s7
	s_waitcnt lgkmcnt(0)
	s_nop 1
	global_load_dword v0, v193, s[8:9] sc1
	s_waitcnt vmcnt(0)
	v_cmp_eq_u32_e32 vcc, v0, v1
	s_and_saveexec_b64 s[6:7], vcc
	s_cbranch_execz .LBB0_3583
	s_mov_b32 s21, 1
	s_mov_b64 s[10:11], 0
	s_branch .LBB0_3574

.LBB0_3682:
	s_or_b64 exec, exec, s[6:7]
	v_cvt_f32_u32_e32 v4, v2
	s_waitcnt vmcnt(0)
	v_readfirstlane_b32 s4, v3
	v_sub_u32_e32 v3, 0, v2
	v_rcp_iflag_f32_e32 v4, v4
	v_add_u32_e32 v5, s4, v1
	v_mul_f32_e32 v4, 0x4f7ffffe, v4
	v_cvt_u32_f32_e32 v4, v4
	v_mul_lo_u32 v1, v3, v4
	v_mul_hi_u32 v1, v4, v1
	v_add_u32_e32 v1, v4, v1
	v_mul_hi_u32 v1, v5, v1
	v_mul_lo_u32 v3, v1, v2
	v_sub_u32_e32 v3, v5, v3
	v_add_u32_e32 v4, 1, v1
	v_cmp_ge_u32_e32 vcc, v3, v2
	s_nop 1
	v_cndmask_b32_e32 v1, v1, v4, vcc
	v_sub_u32_e32 v4, v3, v2
	v_cndmask_b32_e32 v3, v3, v4, vcc
	v_add_u32_e32 v4, 1, v1
	v_cmp_ge_u32_e32 vcc, v3, v2
	v_add_u32_e32 v3, 1, v5
	s_nop 0
	v_cndmask_b32_e32 v1, v1, v4, vcc
	v_mul_lo_u32 v4, v2, v1
	v_add_u32_e32 v2, v4, v2
	v_cmp_ne_u32_e32 vcc, v3, v2
	s_and_saveexec_b64 s[4:5], vcc
	s_xor_b64 s[4:5], exec, s[4:5]
	s_cbranch_execz .LBB0_3696
	s_movk_i32 s92, 0xd40
	s_lshl_b64 s[6:7], s[92:93], 2
	v_readlane_b32 s10, v253, 10
	v_readlane_b32 s11, v253, 11
	s_add_u32 s10, s10, s6
	s_addc_u32 s11, s11, s7
	s_waitcnt lgkmcnt(0)
	s_nop 1
	global_load_dword v0, v193, s[10:11] sc1
	s_waitcnt vmcnt(0)
	v_cmp_eq_u32_e32 vcc, v0, v1
	s_and_saveexec_b64 s[6:7], vcc
	s_cbranch_execz .LBB0_3695
	s_mov_b32 s23, 1
	s_mov_b64 s[12:13], 0
	s_branch .LBB0_3686
